# scan step: second v_cvt_pkrtz of the (sa,v) pair replaced by v_mov of the first result (cheaper op on the serial chain)
# speedup vs baseline: 1.0077x; 1.0077x over previous
.LBB0_120:
	s_bitcmp1_b32 s8, 0
	s_cselect_b32 s6, 0xc100, 0
	s_add_i32 s6, s6, 0
	s_add_i32 s7, s6, 0x1000
	v_mov_b32_e32 v0, s24
	v_mov_b32_e32 v2, s7
	v_cndmask_b32_e64 v0, v0, v2, s[42:43]
	v_mov_b32_e32 v2, s6
	v_cndmask_b32_e64 v0, v0, v2, s[40:41]
	v_add_u32_e32 v156, v0, v107
	v_lshl_add_u32 v146, v110, 2, s6
	v_lshl_add_u32 v0, v108, 2, s6
	v_and_b32_e32 v59, 3, v240
	v_lshrrev_b32_e32 v58, 4, v240
	v_lshl_add_u32 v59, v58, 2, v59
	v_lshl_add_u32 v59, v59, 4, s6
	v_mov_b32_e32 v57, 0x10200
	v_lshl_add_u32 v57, v240, 2, v57
	v_cndmask_b32_e64 v57, v57, v0, s[44:45]
	v_mov_b32_e32 v31, 0
	v_mov_b32_e32 v32, 0
	ds_read_b128 v[2:5], v156
	ds_read_b128 v[6:9], v156 offset:64
	ds_read_b128 v[18:21], v59 offset:16384
	ds_read_b32 v26, v0 offset:24576
	v_add_u32_e32 v58, v156, v109
	ds_read_b128 v[10:13], v58
	ds_read_b128 v[14:17], v58 offset:64
	ds_read_b128 v[22:25], v59 offset:16640
	ds_read_b32 v27, v0 offset:24832
	ds_read_b128 v[40:43], v146 offset:8192
	ds_read_b128 v[44:47], v146 offset:8208
	ds_read_b128 v[48:51], v146 offset:8320
	ds_read_b128 v[52:55], v146 offset:8336
	v_cvt_pkrtz_f16_f32 v68, v82, v83
	v_cvt_pkrtz_f16_f32 v69, v84, v85
	v_cvt_pkrtz_f16_f32 v70, v86, v87
	v_cvt_pkrtz_f16_f32 v71, v88, v89
	v_cvt_pkrtz_f16_f32 v72, v90, v91
	v_cvt_pkrtz_f16_f32 v73, v92, v93
	s_waitcnt lgkmcnt(8)
	v_mfma_f32_16x16x32_f16 v[64:67], v[2:5], v[68:71], 0
	v_cvt_pkrtz_f16_f32 v74, v94, v95
	v_cvt_pkrtz_f16_f32 v75, v96, v97
	s_nop 1
	v_mfma_f32_16x16x32_f16 v[64:67], v[6:9], v[72:75], v[64:67]
	v_add_u32_e32 v58, v156, v120
	ds_read_b128 v[98:101], v58
	ds_read_b128 v[102:105], v58 offset:64
	ds_read_b128 v[60:63], v59 offset:16896
	ds_read_b32 v29, v0 offset:25088
	s_waitcnt lgkmcnt(10)
	s_nop 1
	v_cvt_pkrtz_f16_f32 v30, v64, v26
	v_mov_b32_e32 v33, v30
	ds_write2st64_b32 v57, v65, v64 offset0:129 offset1:161
	v_mfma_f32_4x4x4_16b_f16 v[82:85], v[18:19], v[30:31], v[82:85]
	v_mfma_f32_4x4x4_16b_f16 v[86:89], v[18:19], v[32:33], v[86:89]
	v_mfma_f32_4x4x4_16b_f16 v[90:93], v[20:21], v[30:31], v[90:93]
	v_mfma_f32_4x4x4_16b_f16 v[94:97], v[20:21], v[32:33], v[94:97]
	s_nop 1
	v_cvt_pkrtz_f16_f32 v68, v82, v83
	v_cvt_pkrtz_f16_f32 v69, v84, v85
	v_cvt_pkrtz_f16_f32 v70, v86, v87
	v_cvt_pkrtz_f16_f32 v71, v88, v89
	v_cvt_pkrtz_f16_f32 v72, v90, v91
	v_cvt_pkrtz_f16_f32 v73, v92, v93
	s_waitcnt lgkmcnt(8)
	v_mfma_f32_16x16x32_f16 v[64:67], v[10:13], v[68:71], 0
	v_cvt_pkrtz_f16_f32 v74, v94, v95
	v_cvt_pkrtz_f16_f32 v75, v96, v97
	s_nop 1
	v_mfma_f32_16x16x32_f16 v[64:67], v[14:17], v[72:75], v[64:67]
	v_add_u32_e32 v58, v156, v121
	ds_read_b128 v[2:5], v58
	ds_read_b128 v[6:9], v58 offset:64
	ds_read_b128 v[18:21], v59 offset:17152
	ds_read_b32 v26, v0 offset:25344
	s_waitcnt lgkmcnt(10)
	s_nop 1
	v_cvt_pkrtz_f16_f32 v30, v64, v27
	v_mov_b32_e32 v33, v30
	ds_write2st64_b32 v57, v65, v64 offset0:130 offset1:162
	v_mfma_f32_4x4x4_16b_f16 v[82:85], v[22:23], v[30:31], v[82:85]
	v_mfma_f32_4x4x4_16b_f16 v[86:89], v[22:23], v[32:33], v[86:89]
	v_mfma_f32_4x4x4_16b_f16 v[90:93], v[24:25], v[30:31], v[90:93]
	v_mfma_f32_4x4x4_16b_f16 v[94:97], v[24:25], v[32:33], v[94:97]
	s_nop 1
	v_cvt_pkrtz_f16_f32 v68, v82, v83
	v_cvt_pkrtz_f16_f32 v69, v84, v85
	v_cvt_pkrtz_f16_f32 v70, v86, v87
	v_cvt_pkrtz_f16_f32 v71, v88, v89
	v_cvt_pkrtz_f16_f32 v72, v90, v91
	v_cvt_pkrtz_f16_f32 v73, v92, v93
	s_waitcnt lgkmcnt(8)
	v_mfma_f32_16x16x32_f16 v[64:67], v[98:101], v[68:71], 0
	v_cvt_pkrtz_f16_f32 v74, v94, v95
	v_cvt_pkrtz_f16_f32 v75, v96, v97
	s_nop 1
	v_mfma_f32_16x16x32_f16 v[64:67], v[102:105], v[72:75], v[64:67]
	v_add_u32_e32 v58, v156, v122
	ds_read_b128 v[10:13], v58
	ds_read_b128 v[14:17], v58 offset:64
	ds_read_b128 v[22:25], v59 offset:17408
	ds_read_b32 v27, v0 offset:25600
	s_waitcnt lgkmcnt(10)
	s_nop 1
	v_cvt_pkrtz_f16_f32 v30, v64, v29
	v_mov_b32_e32 v33, v30
	ds_write2st64_b32 v57, v65, v64 offset0:131 offset1:163
	v_mfma_f32_4x4x4_16b_f16 v[82:85], v[60:61], v[30:31], v[82:85]
	v_mfma_f32_4x4x4_16b_f16 v[86:89], v[60:61], v[32:33], v[86:89]
	v_mfma_f32_4x4x4_16b_f16 v[90:93], v[62:63], v[30:31], v[90:93]
	v_mfma_f32_4x4x4_16b_f16 v[94:97], v[62:63], v[32:33], v[94:97]
	s_nop 1
	v_cvt_pkrtz_f16_f32 v68, v82, v83
	v_cvt_pkrtz_f16_f32 v69, v84, v85
	v_cvt_pkrtz_f16_f32 v70, v86, v87
	v_cvt_pkrtz_f16_f32 v71, v88, v89
	v_cvt_pkrtz_f16_f32 v72, v90, v91
	v_cvt_pkrtz_f16_f32 v73, v92, v93
	s_waitcnt lgkmcnt(8)
	v_mfma_f32_16x16x32_f16 v[64:67], v[2:5], v[68:71], 0
	v_cvt_pkrtz_f16_f32 v74, v94, v95
	v_cvt_pkrtz_f16_f32 v75, v96, v97
	s_nop 1
	v_mfma_f32_16x16x32_f16 v[64:67], v[6:9], v[72:75], v[64:67]
	v_add_u32_e32 v58, v156, v123
	ds_read_b128 v[98:101], v58
	ds_read_b128 v[102:105], v58 offset:64
	ds_read_b128 v[60:63], v59 offset:17664
	ds_read_b32 v29, v0 offset:25856
	s_waitcnt lgkmcnt(10)
	s_nop 1
	v_cvt_pkrtz_f16_f32 v30, v64, v26
	v_mov_b32_e32 v33, v30
	ds_write2st64_b32 v57, v65, v64 offset0:132 offset1:164
	v_mfma_f32_4x4x4_16b_f16 v[82:85], v[18:19], v[30:31], v[82:85]
	v_mfma_f32_4x4x4_16b_f16 v[86:89], v[18:19], v[32:33], v[86:89]
	v_mfma_f32_4x4x4_16b_f16 v[90:93], v[20:21], v[30:31], v[90:93]
	v_mfma_f32_4x4x4_16b_f16 v[94:97], v[20:21], v[32:33], v[94:97]
	s_nop 1
	v_cvt_pkrtz_f16_f32 v68, v82, v83
	v_cvt_pkrtz_f16_f32 v69, v84, v85
	v_cvt_pkrtz_f16_f32 v70, v86, v87
	v_cvt_pkrtz_f16_f32 v71, v88, v89
	v_cvt_pkrtz_f16_f32 v72, v90, v91
	v_cvt_pkrtz_f16_f32 v73, v92, v93
	s_waitcnt lgkmcnt(8)
	v_mfma_f32_16x16x32_f16 v[64:67], v[10:13], v[68:71], 0
	v_cvt_pkrtz_f16_f32 v74, v94, v95
	v_cvt_pkrtz_f16_f32 v75, v96, v97
	s_nop 1
	v_mfma_f32_16x16x32_f16 v[64:67], v[14:17], v[72:75], v[64:67]
	v_add_u32_e32 v58, v156, v124
	ds_read_b128 v[2:5], v58
	ds_read_b128 v[6:9], v58 offset:64
	ds_read_b128 v[18:21], v59 offset:17920
	ds_read_b32 v26, v0 offset:26112
	s_waitcnt lgkmcnt(10)
	s_nop 1
	v_cvt_pkrtz_f16_f32 v30, v64, v27
	v_mov_b32_e32 v33, v30
	ds_write2st64_b32 v57, v65, v64 offset0:133 offset1:165
	v_mfma_f32_4x4x4_16b_f16 v[82:85], v[22:23], v[30:31], v[82:85]
	v_mfma_f32_4x4x4_16b_f16 v[86:89], v[22:23], v[32:33], v[86:89]
	v_mfma_f32_4x4x4_16b_f16 v[90:93], v[24:25], v[30:31], v[90:93]
	v_mfma_f32_4x4x4_16b_f16 v[94:97], v[24:25], v[32:33], v[94:97]
	s_nop 1
	v_cvt_pkrtz_f16_f32 v68, v82, v83
	v_cvt_pkrtz_f16_f32 v69, v84, v85
	v_cvt_pkrtz_f16_f32 v70, v86, v87
	v_cvt_pkrtz_f16_f32 v71, v88, v89
	v_cvt_pkrtz_f16_f32 v72, v90, v91
	v_cvt_pkrtz_f16_f32 v73, v92, v93
	s_waitcnt lgkmcnt(8)
	v_mfma_f32_16x16x32_f16 v[64:67], v[98:101], v[68:71], 0
	v_cvt_pkrtz_f16_f32 v74, v94, v95
	v_cvt_pkrtz_f16_f32 v75, v96, v97
	s_nop 1
	v_mfma_f32_16x16x32_f16 v[64:67], v[102:105], v[72:75], v[64:67]
	v_add_u32_e32 v58, v156, v125
	ds_read_b128 v[10:13], v58
	ds_read_b128 v[14:17], v58 offset:64
	ds_read_b128 v[22:25], v59 offset:18176
	ds_read_b32 v27, v0 offset:26368
	s_waitcnt lgkmcnt(10)
	s_nop 1
	v_cvt_pkrtz_f16_f32 v30, v64, v29
	v_mov_b32_e32 v33, v30
	ds_write2st64_b32 v57, v65, v64 offset0:134 offset1:166
	v_mfma_f32_4x4x4_16b_f16 v[82:85], v[60:61], v[30:31], v[82:85]
	v_mfma_f32_4x4x4_16b_f16 v[86:89], v[60:61], v[32:33], v[86:89]
	v_mfma_f32_4x4x4_16b_f16 v[90:93], v[62:63], v[30:31], v[90:93]
	v_mfma_f32_4x4x4_16b_f16 v[94:97], v[62:63], v[32:33], v[94:97]
	s_nop 1
	v_cvt_pkrtz_f16_f32 v68, v82, v83
	v_cvt_pkrtz_f16_f32 v69, v84, v85
	v_cvt_pkrtz_f16_f32 v70, v86, v87
	v_cvt_pkrtz_f16_f32 v71, v88, v89
	v_cvt_pkrtz_f16_f32 v72, v90, v91
	v_cvt_pkrtz_f16_f32 v73, v92, v93
	s_waitcnt lgkmcnt(8)
	v_mfma_f32_16x16x32_f16 v[64:67], v[2:5], v[68:71], 0
	v_cvt_pkrtz_f16_f32 v74, v94, v95
	v_cvt_pkrtz_f16_f32 v75, v96, v97
	s_nop 1
	v_mfma_f32_16x16x32_f16 v[64:67], v[6:9], v[72:75], v[64:67]
	v_add_u32_e32 v58, v156, v126
	ds_read_b128 v[98:101], v58
	ds_read_b128 v[102:105], v58 offset:64
	ds_read_b128 v[60:63], v59 offset:18432
	ds_read_b32 v29, v0 offset:26624
	s_waitcnt lgkmcnt(10)
	s_nop 1
	v_cvt_pkrtz_f16_f32 v30, v64, v26
	v_mov_b32_e32 v33, v30
	ds_write2st64_b32 v57, v65, v64 offset0:135 offset1:167
	v_mfma_f32_4x4x4_16b_f16 v[82:85], v[18:19], v[30:31], v[82:85]
	v_mfma_f32_4x4x4_16b_f16 v[86:89], v[18:19], v[32:33], v[86:89]
	v_mfma_f32_4x4x4_16b_f16 v[90:93], v[20:21], v[30:31], v[90:93]
	v_mfma_f32_4x4x4_16b_f16 v[94:97], v[20:21], v[32:33], v[94:97]
	s_nop 1
	v_cvt_pkrtz_f16_f32 v68, v82, v83
	v_cvt_pkrtz_f16_f32 v69, v84, v85
	v_cvt_pkrtz_f16_f32 v70, v86, v87
	v_cvt_pkrtz_f16_f32 v71, v88, v89
	v_cvt_pkrtz_f16_f32 v72, v90, v91
	v_cvt_pkrtz_f16_f32 v73, v92, v93
	s_waitcnt lgkmcnt(8)
	v_mfma_f32_16x16x32_f16 v[64:67], v[10:13], v[68:71], 0
	v_cvt_pkrtz_f16_f32 v74, v94, v95
	v_cvt_pkrtz_f16_f32 v75, v96, v97
	s_nop 1
	v_mfma_f32_16x16x32_f16 v[64:67], v[14:17], v[72:75], v[64:67]
	v_add_u32_e32 v58, v156, v127
	ds_read_b128 v[2:5], v58
	ds_read_b128 v[6:9], v58 offset:64
	ds_read_b128 v[18:21], v59 offset:18688
	ds_read_b32 v26, v0 offset:26880
	s_waitcnt lgkmcnt(10)
	s_nop 1
	v_cvt_pkrtz_f16_f32 v30, v64, v27
	v_mov_b32_e32 v33, v30
	ds_write2st64_b32 v57, v65, v64 offset0:136 offset1:168
	v_mfma_f32_4x4x4_16b_f16 v[82:85], v[22:23], v[30:31], v[82:85]
	v_mfma_f32_4x4x4_16b_f16 v[86:89], v[22:23], v[32:33], v[86:89]
	v_mfma_f32_4x4x4_16b_f16 v[90:93], v[24:25], v[30:31], v[90:93]
	v_mfma_f32_4x4x4_16b_f16 v[94:97], v[24:25], v[32:33], v[94:97]
	s_nop 1
	v_mul_f32_e32 v82, v82, v40
	v_mul_f32_e32 v83, v83, v41
	v_mul_f32_e32 v84, v84, v42
	v_mul_f32_e32 v85, v85, v43
	v_mul_f32_e32 v86, v86, v44
	v_mul_f32_e32 v87, v87, v45
	v_mul_f32_e32 v88, v88, v46
	v_mul_f32_e32 v89, v89, v47
	v_mul_f32_e32 v90, v90, v48
	v_mul_f32_e32 v91, v91, v49
	v_mul_f32_e32 v92, v92, v50
	v_mul_f32_e32 v93, v93, v51
	v_mul_f32_e32 v94, v94, v52
	v_mul_f32_e32 v95, v95, v53
	v_mul_f32_e32 v96, v96, v54
	v_mul_f32_e32 v97, v97, v55
	ds_read_b128 v[40:43], v146 offset:8448
	ds_read_b128 v[44:47], v146 offset:8464
	ds_read_b128 v[48:51], v146 offset:8576
	ds_read_b128 v[52:55], v146 offset:8592
	v_cvt_pkrtz_f16_f32 v68, v82, v83
	v_cvt_pkrtz_f16_f32 v69, v84, v85
	v_cvt_pkrtz_f16_f32 v70, v86, v87
	v_cvt_pkrtz_f16_f32 v71, v88, v89
	v_cvt_pkrtz_f16_f32 v72, v90, v91
	v_cvt_pkrtz_f16_f32 v73, v92, v93
	s_waitcnt lgkmcnt(8)
	v_mfma_f32_16x16x32_f16 v[64:67], v[98:101], v[68:71], 0
	v_cvt_pkrtz_f16_f32 v74, v94, v95
	v_cvt_pkrtz_f16_f32 v75, v96, v97
	s_nop 1
	v_mfma_f32_16x16x32_f16 v[64:67], v[102:105], v[72:75], v[64:67]
	v_add_u32_e32 v58, v156, v128
	ds_read_b128 v[10:13], v58
	ds_read_b128 v[14:17], v58 offset:64
	ds_read_b128 v[22:25], v59 offset:18944
	ds_read_b32 v27, v0 offset:27136
	s_waitcnt lgkmcnt(10)
	s_nop 1
	v_cvt_pkrtz_f16_f32 v30, v64, v29
	v_mov_b32_e32 v33, v30
	ds_write2st64_b32 v57, v65, v64 offset0:137 offset1:169
	v_mfma_f32_4x4x4_16b_f16 v[82:85], v[60:61], v[30:31], v[82:85]
	v_mfma_f32_4x4x4_16b_f16 v[86:89], v[60:61], v[32:33], v[86:89]
	v_mfma_f32_4x4x4_16b_f16 v[90:93], v[62:63], v[30:31], v[90:93]
	v_mfma_f32_4x4x4_16b_f16 v[94:97], v[62:63], v[32:33], v[94:97]
	s_nop 1
	v_cvt_pkrtz_f16_f32 v68, v82, v83
	v_cvt_pkrtz_f16_f32 v69, v84, v85
	v_cvt_pkrtz_f16_f32 v70, v86, v87
	v_cvt_pkrtz_f16_f32 v71, v88, v89
	v_cvt_pkrtz_f16_f32 v72, v90, v91
	v_cvt_pkrtz_f16_f32 v73, v92, v93
	s_waitcnt lgkmcnt(8)
	v_mfma_f32_16x16x32_f16 v[64:67], v[2:5], v[68:71], 0
	v_cvt_pkrtz_f16_f32 v74, v94, v95
	v_cvt_pkrtz_f16_f32 v75, v96, v97
	s_nop 1
	v_mfma_f32_16x16x32_f16 v[64:67], v[6:9], v[72:75], v[64:67]
	v_add_u32_e32 v58, v156, v129
	ds_read_b128 v[98:101], v58
	ds_read_b128 v[102:105], v58 offset:64
	ds_read_b128 v[60:63], v59 offset:19200
	ds_read_b32 v29, v0 offset:27392
	s_waitcnt lgkmcnt(10)
	s_nop 1
	v_cvt_pkrtz_f16_f32 v30, v64, v26
	v_mov_b32_e32 v33, v30
	ds_write2st64_b32 v57, v65, v64 offset0:138 offset1:170
	v_mfma_f32_4x4x4_16b_f16 v[82:85], v[18:19], v[30:31], v[82:85]
	v_mfma_f32_4x4x4_16b_f16 v[86:89], v[18:19], v[32:33], v[86:89]
	v_mfma_f32_4x4x4_16b_f16 v[90:93], v[20:21], v[30:31], v[90:93]
	v_mfma_f32_4x4x4_16b_f16 v[94:97], v[20:21], v[32:33], v[94:97]
	s_nop 1
	v_cvt_pkrtz_f16_f32 v68, v82, v83
	v_cvt_pkrtz_f16_f32 v69, v84, v85
	v_cvt_pkrtz_f16_f32 v70, v86, v87
	v_cvt_pkrtz_f16_f32 v71, v88, v89
	v_cvt_pkrtz_f16_f32 v72, v90, v91
	v_cvt_pkrtz_f16_f32 v73, v92, v93
	s_waitcnt lgkmcnt(8)
	v_mfma_f32_16x16x32_f16 v[64:67], v[10:13], v[68:71], 0
	v_cvt_pkrtz_f16_f32 v74, v94, v95
	v_cvt_pkrtz_f16_f32 v75, v96, v97
	s_nop 1
	v_mfma_f32_16x16x32_f16 v[64:67], v[14:17], v[72:75], v[64:67]
	v_add_u32_e32 v58, v156, v130
	ds_read_b128 v[2:5], v58
	ds_read_b128 v[6:9], v58 offset:64
	ds_read_b128 v[18:21], v59 offset:19456
	ds_read_b32 v26, v0 offset:27648
	s_waitcnt lgkmcnt(10)
	s_nop 1
	v_cvt_pkrtz_f16_f32 v30, v64, v27
	v_mov_b32_e32 v33, v30
	ds_write2st64_b32 v57, v65, v64 offset0:139 offset1:171
	v_mfma_f32_4x4x4_16b_f16 v[82:85], v[22:23], v[30:31], v[82:85]
	v_mfma_f32_4x4x4_16b_f16 v[86:89], v[22:23], v[32:33], v[86:89]
	v_mfma_f32_4x4x4_16b_f16 v[90:93], v[24:25], v[30:31], v[90:93]
	v_mfma_f32_4x4x4_16b_f16 v[94:97], v[24:25], v[32:33], v[94:97]
	s_nop 1
	v_cvt_pkrtz_f16_f32 v68, v82, v83
	v_cvt_pkrtz_f16_f32 v69, v84, v85
	v_cvt_pkrtz_f16_f32 v70, v86, v87
	v_cvt_pkrtz_f16_f32 v71, v88, v89
	v_cvt_pkrtz_f16_f32 v72, v90, v91
	v_cvt_pkrtz_f16_f32 v73, v92, v93
	s_waitcnt lgkmcnt(8)
	v_mfma_f32_16x16x32_f16 v[64:67], v[98:101], v[68:71], 0
	v_cvt_pkrtz_f16_f32 v74, v94, v95
	v_cvt_pkrtz_f16_f32 v75, v96, v97
	s_nop 1
	v_mfma_f32_16x16x32_f16 v[64:67], v[102:105], v[72:75], v[64:67]
	v_add_u32_e32 v58, v156, v131
	ds_read_b128 v[10:13], v58
	ds_read_b128 v[14:17], v58 offset:64
	ds_read_b128 v[22:25], v59 offset:19712
	ds_read_b32 v27, v0 offset:27904
	s_waitcnt lgkmcnt(10)
	s_nop 1
	v_cvt_pkrtz_f16_f32 v30, v64, v29
	v_mov_b32_e32 v33, v30
	ds_write2st64_b32 v57, v65, v64 offset0:140 offset1:172
	v_mfma_f32_4x4x4_16b_f16 v[82:85], v[60:61], v[30:31], v[82:85]
	v_mfma_f32_4x4x4_16b_f16 v[86:89], v[60:61], v[32:33], v[86:89]
	v_mfma_f32_4x4x4_16b_f16 v[90:93], v[62:63], v[30:31], v[90:93]
	v_mfma_f32_4x4x4_16b_f16 v[94:97], v[62:63], v[32:33], v[94:97]
	s_nop 1
	v_cvt_pkrtz_f16_f32 v68, v82, v83
	v_cvt_pkrtz_f16_f32 v69, v84, v85
	v_cvt_pkrtz_f16_f32 v70, v86, v87
	v_cvt_pkrtz_f16_f32 v71, v88, v89
	v_cvt_pkrtz_f16_f32 v72, v90, v91
	v_cvt_pkrtz_f16_f32 v73, v92, v93
	s_waitcnt lgkmcnt(8)
	v_mfma_f32_16x16x32_f16 v[64:67], v[2:5], v[68:71], 0
	v_cvt_pkrtz_f16_f32 v74, v94, v95
	v_cvt_pkrtz_f16_f32 v75, v96, v97
	s_nop 1
	v_mfma_f32_16x16x32_f16 v[64:67], v[6:9], v[72:75], v[64:67]
	v_add_u32_e32 v58, v156, v132
	ds_read_b128 v[98:101], v58
	ds_read_b128 v[102:105], v58 offset:64
	ds_read_b128 v[60:63], v59 offset:19968
	ds_read_b32 v29, v0 offset:28160
	s_waitcnt lgkmcnt(10)
	s_nop 1
	v_cvt_pkrtz_f16_f32 v30, v64, v26
	v_mov_b32_e32 v33, v30
	ds_write2st64_b32 v57, v65, v64 offset0:141 offset1:173
	v_mfma_f32_4x4x4_16b_f16 v[82:85], v[18:19], v[30:31], v[82:85]
	v_mfma_f32_4x4x4_16b_f16 v[86:89], v[18:19], v[32:33], v[86:89]
	v_mfma_f32_4x4x4_16b_f16 v[90:93], v[20:21], v[30:31], v[90:93]
	v_mfma_f32_4x4x4_16b_f16 v[94:97], v[20:21], v[32:33], v[94:97]
	s_nop 1
	v_cvt_pkrtz_f16_f32 v68, v82, v83
	v_cvt_pkrtz_f16_f32 v69, v84, v85
	v_cvt_pkrtz_f16_f32 v70, v86, v87
	v_cvt_pkrtz_f16_f32 v71, v88, v89
	v_cvt_pkrtz_f16_f32 v72, v90, v91
	v_cvt_pkrtz_f16_f32 v73, v92, v93
	s_waitcnt lgkmcnt(8)
	v_mfma_f32_16x16x32_f16 v[64:67], v[10:13], v[68:71], 0
	v_cvt_pkrtz_f16_f32 v74, v94, v95
	v_cvt_pkrtz_f16_f32 v75, v96, v97
	s_nop 1
	v_mfma_f32_16x16x32_f16 v[64:67], v[14:17], v[72:75], v[64:67]
	v_add_u32_e32 v58, v156, v133
	ds_read_b128 v[2:5], v58
	ds_read_b128 v[6:9], v58 offset:64
	ds_read_b128 v[18:21], v59 offset:20224
	ds_read_b32 v26, v0 offset:28416
	s_waitcnt lgkmcnt(10)
	s_nop 1
	v_cvt_pkrtz_f16_f32 v30, v64, v27
	v_mov_b32_e32 v33, v30
	ds_write2st64_b32 v57, v65, v64 offset0:142 offset1:174
	v_mfma_f32_4x4x4_16b_f16 v[82:85], v[22:23], v[30:31], v[82:85]
	v_mfma_f32_4x4x4_16b_f16 v[86:89], v[22:23], v[32:33], v[86:89]
	v_mfma_f32_4x4x4_16b_f16 v[90:93], v[24:25], v[30:31], v[90:93]
	v_mfma_f32_4x4x4_16b_f16 v[94:97], v[24:25], v[32:33], v[94:97]
	s_nop 1
	v_cvt_pkrtz_f16_f32 v68, v82, v83
	v_cvt_pkrtz_f16_f32 v69, v84, v85
	v_cvt_pkrtz_f16_f32 v70, v86, v87
	v_cvt_pkrtz_f16_f32 v71, v88, v89
	v_cvt_pkrtz_f16_f32 v72, v90, v91
	v_cvt_pkrtz_f16_f32 v73, v92, v93
	s_waitcnt lgkmcnt(8)
	v_mfma_f32_16x16x32_f16 v[64:67], v[98:101], v[68:71], 0
	v_cvt_pkrtz_f16_f32 v74, v94, v95
	v_cvt_pkrtz_f16_f32 v75, v96, v97
	s_nop 1
	v_mfma_f32_16x16x32_f16 v[64:67], v[102:105], v[72:75], v[64:67]
	v_add_u32_e32 v58, v156, v134
	ds_read_b128 v[10:13], v58
	ds_read_b128 v[14:17], v58 offset:64
	ds_read_b128 v[22:25], v59 offset:20480
	ds_read_b32 v27, v0 offset:28672
	s_waitcnt lgkmcnt(10)
	s_nop 1
	v_cvt_pkrtz_f16_f32 v30, v64, v29
	v_mov_b32_e32 v33, v30
	ds_write2st64_b32 v57, v65, v64 offset0:143 offset1:175
	v_mfma_f32_4x4x4_16b_f16 v[82:85], v[60:61], v[30:31], v[82:85]
	v_mfma_f32_4x4x4_16b_f16 v[86:89], v[60:61], v[32:33], v[86:89]
	v_mfma_f32_4x4x4_16b_f16 v[90:93], v[62:63], v[30:31], v[90:93]
	v_mfma_f32_4x4x4_16b_f16 v[94:97], v[62:63], v[32:33], v[94:97]
	s_nop 1
	v_cvt_pkrtz_f16_f32 v68, v82, v83
	v_cvt_pkrtz_f16_f32 v69, v84, v85
	v_cvt_pkrtz_f16_f32 v70, v86, v87
	v_cvt_pkrtz_f16_f32 v71, v88, v89
	v_cvt_pkrtz_f16_f32 v72, v90, v91
	v_cvt_pkrtz_f16_f32 v73, v92, v93
	s_waitcnt lgkmcnt(8)
	v_mfma_f32_16x16x32_f16 v[64:67], v[2:5], v[68:71], 0
	v_cvt_pkrtz_f16_f32 v74, v94, v95
	v_cvt_pkrtz_f16_f32 v75, v96, v97
	s_nop 1
	v_mfma_f32_16x16x32_f16 v[64:67], v[6:9], v[72:75], v[64:67]
	v_add_u32_e32 v58, v156, v135
	ds_read_b128 v[98:101], v58
	ds_read_b128 v[102:105], v58 offset:64
	ds_read_b128 v[60:63], v59 offset:20736
	ds_read_b32 v29, v0 offset:28928
	s_waitcnt lgkmcnt(10)
	s_nop 1
	v_cvt_pkrtz_f16_f32 v30, v64, v26
	v_mov_b32_e32 v33, v30
	ds_write2st64_b32 v57, v65, v64 offset0:144 offset1:176
	v_mfma_f32_4x4x4_16b_f16 v[82:85], v[18:19], v[30:31], v[82:85]
	v_mfma_f32_4x4x4_16b_f16 v[86:89], v[18:19], v[32:33], v[86:89]
	v_mfma_f32_4x4x4_16b_f16 v[90:93], v[20:21], v[30:31], v[90:93]
	v_mfma_f32_4x4x4_16b_f16 v[94:97], v[20:21], v[32:33], v[94:97]
	s_nop 1
	v_mul_f32_e32 v82, v82, v40
	v_mul_f32_e32 v83, v83, v41
	v_mul_f32_e32 v84, v84, v42
	v_mul_f32_e32 v85, v85, v43
	v_mul_f32_e32 v86, v86, v44
	v_mul_f32_e32 v87, v87, v45
	v_mul_f32_e32 v88, v88, v46
	v_mul_f32_e32 v89, v89, v47
	v_mul_f32_e32 v90, v90, v48
	v_mul_f32_e32 v91, v91, v49
	v_mul_f32_e32 v92, v92, v50
	v_mul_f32_e32 v93, v93, v51
	v_mul_f32_e32 v94, v94, v52
	v_mul_f32_e32 v95, v95, v53
	v_mul_f32_e32 v96, v96, v54
	v_mul_f32_e32 v97, v97, v55
	ds_read_b128 v[40:43], v146 offset:8704
	ds_read_b128 v[44:47], v146 offset:8720
	ds_read_b128 v[48:51], v146 offset:8832
	ds_read_b128 v[52:55], v146 offset:8848
	v_cvt_pkrtz_f16_f32 v68, v82, v83
	v_cvt_pkrtz_f16_f32 v69, v84, v85
	v_cvt_pkrtz_f16_f32 v70, v86, v87
	v_cvt_pkrtz_f16_f32 v71, v88, v89
	v_cvt_pkrtz_f16_f32 v72, v90, v91
	v_cvt_pkrtz_f16_f32 v73, v92, v93
	s_waitcnt lgkmcnt(8)
	v_mfma_f32_16x16x32_f16 v[64:67], v[10:13], v[68:71], 0
	v_cvt_pkrtz_f16_f32 v74, v94, v95
	v_cvt_pkrtz_f16_f32 v75, v96, v97
	s_nop 1
	v_mfma_f32_16x16x32_f16 v[64:67], v[14:17], v[72:75], v[64:67]
	v_add_u32_e32 v58, v156, v136
	ds_read_b128 v[2:5], v58
	ds_read_b128 v[6:9], v58 offset:64
	ds_read_b128 v[18:21], v59 offset:20992
	ds_read_b32 v26, v0 offset:29184
	s_waitcnt lgkmcnt(10)
	s_nop 1
	v_cvt_pkrtz_f16_f32 v30, v64, v27
	v_mov_b32_e32 v33, v30
	ds_write2st64_b32 v57, v65, v64 offset0:145 offset1:177
	v_mfma_f32_4x4x4_16b_f16 v[82:85], v[22:23], v[30:31], v[82:85]
	v_mfma_f32_4x4x4_16b_f16 v[86:89], v[22:23], v[32:33], v[86:89]
	v_mfma_f32_4x4x4_16b_f16 v[90:93], v[24:25], v[30:31], v[90:93]
	v_mfma_f32_4x4x4_16b_f16 v[94:97], v[24:25], v[32:33], v[94:97]
	s_nop 1
	v_cvt_pkrtz_f16_f32 v68, v82, v83
	v_cvt_pkrtz_f16_f32 v69, v84, v85
	v_cvt_pkrtz_f16_f32 v70, v86, v87
	v_cvt_pkrtz_f16_f32 v71, v88, v89
	v_cvt_pkrtz_f16_f32 v72, v90, v91
	v_cvt_pkrtz_f16_f32 v73, v92, v93
	s_waitcnt lgkmcnt(8)
	v_mfma_f32_16x16x32_f16 v[64:67], v[98:101], v[68:71], 0
	v_cvt_pkrtz_f16_f32 v74, v94, v95
	v_cvt_pkrtz_f16_f32 v75, v96, v97
	s_nop 1
	v_mfma_f32_16x16x32_f16 v[64:67], v[102:105], v[72:75], v[64:67]
	v_add_u32_e32 v58, v156, v137
	ds_read_b128 v[10:13], v58
	ds_read_b128 v[14:17], v58 offset:64
	ds_read_b128 v[22:25], v59 offset:21248
	ds_read_b32 v27, v0 offset:29440
	s_waitcnt lgkmcnt(10)
	s_nop 1
	v_cvt_pkrtz_f16_f32 v30, v64, v29
	v_mov_b32_e32 v33, v30
	ds_write2st64_b32 v57, v65, v64 offset0:146 offset1:178
	v_mfma_f32_4x4x4_16b_f16 v[82:85], v[60:61], v[30:31], v[82:85]
	v_mfma_f32_4x4x4_16b_f16 v[86:89], v[60:61], v[32:33], v[86:89]
	v_mfma_f32_4x4x4_16b_f16 v[90:93], v[62:63], v[30:31], v[90:93]
	v_mfma_f32_4x4x4_16b_f16 v[94:97], v[62:63], v[32:33], v[94:97]
	s_nop 1
	v_cvt_pkrtz_f16_f32 v68, v82, v83
	v_cvt_pkrtz_f16_f32 v69, v84, v85
	v_cvt_pkrtz_f16_f32 v70, v86, v87
	v_cvt_pkrtz_f16_f32 v71, v88, v89
	v_cvt_pkrtz_f16_f32 v72, v90, v91
	v_cvt_pkrtz_f16_f32 v73, v92, v93
	s_waitcnt lgkmcnt(8)
	v_mfma_f32_16x16x32_f16 v[64:67], v[2:5], v[68:71], 0
	v_cvt_pkrtz_f16_f32 v74, v94, v95
	v_cvt_pkrtz_f16_f32 v75, v96, v97
	s_nop 1
	v_mfma_f32_16x16x32_f16 v[64:67], v[6:9], v[72:75], v[64:67]
	v_add_u32_e32 v58, v156, v138
	ds_read_b128 v[98:101], v58
	ds_read_b128 v[102:105], v58 offset:64
	ds_read_b128 v[60:63], v59 offset:21504
	ds_read_b32 v29, v0 offset:29696
	s_waitcnt lgkmcnt(10)
	s_nop 1
	v_cvt_pkrtz_f16_f32 v30, v64, v26
	v_mov_b32_e32 v33, v30
	ds_write2st64_b32 v57, v65, v64 offset0:147 offset1:179
	v_mfma_f32_4x4x4_16b_f16 v[82:85], v[18:19], v[30:31], v[82:85]
	v_mfma_f32_4x4x4_16b_f16 v[86:89], v[18:19], v[32:33], v[86:89]
	v_mfma_f32_4x4x4_16b_f16 v[90:93], v[20:21], v[30:31], v[90:93]
	v_mfma_f32_4x4x4_16b_f16 v[94:97], v[20:21], v[32:33], v[94:97]
	s_nop 1
	v_cvt_pkrtz_f16_f32 v68, v82, v83
	v_cvt_pkrtz_f16_f32 v69, v84, v85
	v_cvt_pkrtz_f16_f32 v70, v86, v87
	v_cvt_pkrtz_f16_f32 v71, v88, v89
	v_cvt_pkrtz_f16_f32 v72, v90, v91
	v_cvt_pkrtz_f16_f32 v73, v92, v93
	s_waitcnt lgkmcnt(8)
	v_mfma_f32_16x16x32_f16 v[64:67], v[10:13], v[68:71], 0
	v_cvt_pkrtz_f16_f32 v74, v94, v95
	v_cvt_pkrtz_f16_f32 v75, v96, v97
	s_nop 1
	v_mfma_f32_16x16x32_f16 v[64:67], v[14:17], v[72:75], v[64:67]
	v_add_u32_e32 v58, v156, v139
	ds_read_b128 v[2:5], v58
	ds_read_b128 v[6:9], v58 offset:64
	ds_read_b128 v[18:21], v59 offset:21760
	ds_read_b32 v26, v0 offset:29952
	s_waitcnt lgkmcnt(10)
	s_nop 1
	v_cvt_pkrtz_f16_f32 v30, v64, v27
	v_mov_b32_e32 v33, v30
	ds_write2st64_b32 v57, v65, v64 offset0:148 offset1:180
	v_mfma_f32_4x4x4_16b_f16 v[82:85], v[22:23], v[30:31], v[82:85]
	v_mfma_f32_4x4x4_16b_f16 v[86:89], v[22:23], v[32:33], v[86:89]
	v_mfma_f32_4x4x4_16b_f16 v[90:93], v[24:25], v[30:31], v[90:93]
	v_mfma_f32_4x4x4_16b_f16 v[94:97], v[24:25], v[32:33], v[94:97]
	s_nop 1
	v_cvt_pkrtz_f16_f32 v68, v82, v83
	v_cvt_pkrtz_f16_f32 v69, v84, v85
	v_cvt_pkrtz_f16_f32 v70, v86, v87
	v_cvt_pkrtz_f16_f32 v71, v88, v89
	v_cvt_pkrtz_f16_f32 v72, v90, v91
	v_cvt_pkrtz_f16_f32 v73, v92, v93
	s_waitcnt lgkmcnt(8)
	v_mfma_f32_16x16x32_f16 v[64:67], v[98:101], v[68:71], 0
	v_cvt_pkrtz_f16_f32 v74, v94, v95
	v_cvt_pkrtz_f16_f32 v75, v96, v97
	s_nop 1
	v_mfma_f32_16x16x32_f16 v[64:67], v[102:105], v[72:75], v[64:67]
	v_add_u32_e32 v58, v156, v140
	ds_read_b128 v[10:13], v58
	ds_read_b128 v[14:17], v58 offset:64
	ds_read_b128 v[22:25], v59 offset:22016
	ds_read_b32 v27, v0 offset:30208
	s_waitcnt lgkmcnt(10)
	s_nop 1
	v_cvt_pkrtz_f16_f32 v30, v64, v29
	v_mov_b32_e32 v33, v30
	ds_write2st64_b32 v57, v65, v64 offset0:149 offset1:181
	v_mfma_f32_4x4x4_16b_f16 v[82:85], v[60:61], v[30:31], v[82:85]
	v_mfma_f32_4x4x4_16b_f16 v[86:89], v[60:61], v[32:33], v[86:89]
	v_mfma_f32_4x4x4_16b_f16 v[90:93], v[62:63], v[30:31], v[90:93]
	v_mfma_f32_4x4x4_16b_f16 v[94:97], v[62:63], v[32:33], v[94:97]
	s_nop 1
	v_cvt_pkrtz_f16_f32 v68, v82, v83
	v_cvt_pkrtz_f16_f32 v69, v84, v85
	v_cvt_pkrtz_f16_f32 v70, v86, v87
	v_cvt_pkrtz_f16_f32 v71, v88, v89
	v_cvt_pkrtz_f16_f32 v72, v90, v91
	v_cvt_pkrtz_f16_f32 v73, v92, v93
	s_waitcnt lgkmcnt(8)
	v_mfma_f32_16x16x32_f16 v[64:67], v[2:5], v[68:71], 0
	v_cvt_pkrtz_f16_f32 v74, v94, v95
	v_cvt_pkrtz_f16_f32 v75, v96, v97
	s_nop 1
	v_mfma_f32_16x16x32_f16 v[64:67], v[6:9], v[72:75], v[64:67]
	v_add_u32_e32 v58, v156, v141
	ds_read_b128 v[98:101], v58
	ds_read_b128 v[102:105], v58 offset:64
	ds_read_b128 v[60:63], v59 offset:22272
	ds_read_b32 v29, v0 offset:30464
	s_waitcnt lgkmcnt(10)
	s_nop 1
	v_cvt_pkrtz_f16_f32 v30, v64, v26
	v_mov_b32_e32 v33, v30
	ds_write2st64_b32 v57, v65, v64 offset0:150 offset1:182
	v_mfma_f32_4x4x4_16b_f16 v[82:85], v[18:19], v[30:31], v[82:85]
	v_mfma_f32_4x4x4_16b_f16 v[86:89], v[18:19], v[32:33], v[86:89]
	v_mfma_f32_4x4x4_16b_f16 v[90:93], v[20:21], v[30:31], v[90:93]
	v_mfma_f32_4x4x4_16b_f16 v[94:97], v[20:21], v[32:33], v[94:97]
	s_nop 1
	v_cvt_pkrtz_f16_f32 v68, v82, v83
	v_cvt_pkrtz_f16_f32 v69, v84, v85
	v_cvt_pkrtz_f16_f32 v70, v86, v87
	v_cvt_pkrtz_f16_f32 v71, v88, v89
	v_cvt_pkrtz_f16_f32 v72, v90, v91
	v_cvt_pkrtz_f16_f32 v73, v92, v93
	s_waitcnt lgkmcnt(8)
	v_mfma_f32_16x16x32_f16 v[64:67], v[10:13], v[68:71], 0
	v_cvt_pkrtz_f16_f32 v74, v94, v95
	v_cvt_pkrtz_f16_f32 v75, v96, v97
	s_nop 1
	v_mfma_f32_16x16x32_f16 v[64:67], v[14:17], v[72:75], v[64:67]
	v_add_u32_e32 v58, v156, v142
	ds_read_b128 v[2:5], v58
	ds_read_b128 v[6:9], v58 offset:64
	ds_read_b128 v[18:21], v59 offset:22528
	ds_read_b32 v26, v0 offset:30720
	s_waitcnt lgkmcnt(10)
	s_nop 1
	v_cvt_pkrtz_f16_f32 v30, v64, v27
	v_mov_b32_e32 v33, v30
	ds_write2st64_b32 v57, v65, v64 offset0:151 offset1:183
	v_mfma_f32_4x4x4_16b_f16 v[82:85], v[22:23], v[30:31], v[82:85]
	v_mfma_f32_4x4x4_16b_f16 v[86:89], v[22:23], v[32:33], v[86:89]
	v_mfma_f32_4x4x4_16b_f16 v[90:93], v[24:25], v[30:31], v[90:93]
	v_mfma_f32_4x4x4_16b_f16 v[94:97], v[24:25], v[32:33], v[94:97]
	s_nop 1
	v_cvt_pkrtz_f16_f32 v68, v82, v83
	v_cvt_pkrtz_f16_f32 v69, v84, v85
	v_cvt_pkrtz_f16_f32 v70, v86, v87
	v_cvt_pkrtz_f16_f32 v71, v88, v89
	v_cvt_pkrtz_f16_f32 v72, v90, v91
	v_cvt_pkrtz_f16_f32 v73, v92, v93
	s_waitcnt lgkmcnt(8)
	v_mfma_f32_16x16x32_f16 v[64:67], v[98:101], v[68:71], 0
	v_cvt_pkrtz_f16_f32 v74, v94, v95
	v_cvt_pkrtz_f16_f32 v75, v96, v97
	s_nop 1
	v_mfma_f32_16x16x32_f16 v[64:67], v[102:105], v[72:75], v[64:67]
	v_add_u32_e32 v58, v156, v143
	ds_read_b128 v[10:13], v58
	ds_read_b128 v[14:17], v58 offset:64
	ds_read_b128 v[22:25], v59 offset:22784
	ds_read_b32 v27, v0 offset:30976
	s_waitcnt lgkmcnt(10)
	s_nop 1
	v_cvt_pkrtz_f16_f32 v30, v64, v29
	v_mov_b32_e32 v33, v30
	ds_write2st64_b32 v57, v65, v64 offset0:152 offset1:184
	v_mfma_f32_4x4x4_16b_f16 v[82:85], v[60:61], v[30:31], v[82:85]
	v_mfma_f32_4x4x4_16b_f16 v[86:89], v[60:61], v[32:33], v[86:89]
	v_mfma_f32_4x4x4_16b_f16 v[90:93], v[62:63], v[30:31], v[90:93]
	v_mfma_f32_4x4x4_16b_f16 v[94:97], v[62:63], v[32:33], v[94:97]
	s_nop 1
	v_mul_f32_e32 v82, v82, v40
	v_mul_f32_e32 v83, v83, v41
	v_mul_f32_e32 v84, v84, v42
	v_mul_f32_e32 v85, v85, v43
	v_mul_f32_e32 v86, v86, v44
	v_mul_f32_e32 v87, v87, v45
	v_mul_f32_e32 v88, v88, v46
	v_mul_f32_e32 v89, v89, v47
	v_mul_f32_e32 v90, v90, v48
	v_mul_f32_e32 v91, v91, v49
	v_mul_f32_e32 v92, v92, v50
	v_mul_f32_e32 v93, v93, v51
	v_mul_f32_e32 v94, v94, v52
	v_mul_f32_e32 v95, v95, v53
	v_mul_f32_e32 v96, v96, v54
	v_mul_f32_e32 v97, v97, v55
	ds_read_b128 v[40:43], v146 offset:8960
	ds_read_b128 v[44:47], v146 offset:8976
	ds_read_b128 v[48:51], v146 offset:9088
	ds_read_b128 v[52:55], v146 offset:9104
	v_cvt_pkrtz_f16_f32 v68, v82, v83
	v_cvt_pkrtz_f16_f32 v69, v84, v85
	v_cvt_pkrtz_f16_f32 v70, v86, v87
	v_cvt_pkrtz_f16_f32 v71, v88, v89
	v_cvt_pkrtz_f16_f32 v72, v90, v91
	v_cvt_pkrtz_f16_f32 v73, v92, v93
	s_waitcnt lgkmcnt(8)
	v_mfma_f32_16x16x32_f16 v[64:67], v[2:5], v[68:71], 0
	v_cvt_pkrtz_f16_f32 v74, v94, v95
	v_cvt_pkrtz_f16_f32 v75, v96, v97
	s_nop 1
	v_mfma_f32_16x16x32_f16 v[64:67], v[6:9], v[72:75], v[64:67]
	v_add_u32_e32 v58, v156, v144
	ds_read_b128 v[98:101], v58
	ds_read_b128 v[102:105], v58 offset:64
	ds_read_b128 v[60:63], v59 offset:23040
	ds_read_b32 v29, v0 offset:31232
	s_waitcnt lgkmcnt(10)
	s_nop 1
	v_cvt_pkrtz_f16_f32 v30, v64, v26
	v_mov_b32_e32 v33, v30
	ds_write2st64_b32 v57, v65, v64 offset0:153 offset1:185
	v_mfma_f32_4x4x4_16b_f16 v[82:85], v[18:19], v[30:31], v[82:85]
	v_mfma_f32_4x4x4_16b_f16 v[86:89], v[18:19], v[32:33], v[86:89]
	v_mfma_f32_4x4x4_16b_f16 v[90:93], v[20:21], v[30:31], v[90:93]
	v_mfma_f32_4x4x4_16b_f16 v[94:97], v[20:21], v[32:33], v[94:97]
	s_nop 1
	v_cvt_pkrtz_f16_f32 v68, v82, v83
	v_cvt_pkrtz_f16_f32 v69, v84, v85
	v_cvt_pkrtz_f16_f32 v70, v86, v87
	v_cvt_pkrtz_f16_f32 v71, v88, v89
	v_cvt_pkrtz_f16_f32 v72, v90, v91
	v_cvt_pkrtz_f16_f32 v73, v92, v93
	s_waitcnt lgkmcnt(8)
	v_mfma_f32_16x16x32_f16 v[64:67], v[10:13], v[68:71], 0
	v_cvt_pkrtz_f16_f32 v74, v94, v95
	v_cvt_pkrtz_f16_f32 v75, v96, v97
	s_nop 1
	v_mfma_f32_16x16x32_f16 v[64:67], v[14:17], v[72:75], v[64:67]
	v_add_u32_e32 v58, v156, v145
	ds_read_b128 v[2:5], v58
	ds_read_b128 v[6:9], v58 offset:64
	ds_read_b128 v[18:21], v59 offset:23296
	ds_read_b32 v26, v0 offset:31488
	s_waitcnt lgkmcnt(10)
	s_nop 1
	v_cvt_pkrtz_f16_f32 v30, v64, v27
	v_mov_b32_e32 v33, v30
	ds_write2st64_b32 v57, v65, v64 offset0:154 offset1:186
	v_mfma_f32_4x4x4_16b_f16 v[82:85], v[22:23], v[30:31], v[82:85]
	v_mfma_f32_4x4x4_16b_f16 v[86:89], v[22:23], v[32:33], v[86:89]
	v_mfma_f32_4x4x4_16b_f16 v[90:93], v[24:25], v[30:31], v[90:93]
	v_mfma_f32_4x4x4_16b_f16 v[94:97], v[24:25], v[32:33], v[94:97]
	s_nop 1
	v_cvt_pkrtz_f16_f32 v68, v82, v83
	v_cvt_pkrtz_f16_f32 v69, v84, v85
	v_cvt_pkrtz_f16_f32 v70, v86, v87
	v_cvt_pkrtz_f16_f32 v71, v88, v89
	v_cvt_pkrtz_f16_f32 v72, v90, v91
	v_cvt_pkrtz_f16_f32 v73, v92, v93
	s_waitcnt lgkmcnt(8)
	v_mfma_f32_16x16x32_f16 v[64:67], v[98:101], v[68:71], 0
	v_cvt_pkrtz_f16_f32 v74, v94, v95
	v_cvt_pkrtz_f16_f32 v75, v96, v97
	s_nop 1
	v_mfma_f32_16x16x32_f16 v[64:67], v[102:105], v[72:75], v[64:67]
	v_add_u32_e32 v58, v156, v148
	ds_read_b128 v[10:13], v58
	ds_read_b128 v[14:17], v58 offset:64
	ds_read_b128 v[22:25], v59 offset:23552
	ds_read_b32 v27, v0 offset:31744
	s_waitcnt lgkmcnt(10)
	s_nop 1
	v_cvt_pkrtz_f16_f32 v30, v64, v29
	v_mov_b32_e32 v33, v30
	ds_write2st64_b32 v57, v65, v64 offset0:155 offset1:187
	v_mfma_f32_4x4x4_16b_f16 v[82:85], v[60:61], v[30:31], v[82:85]
	v_mfma_f32_4x4x4_16b_f16 v[86:89], v[60:61], v[32:33], v[86:89]
	v_mfma_f32_4x4x4_16b_f16 v[90:93], v[62:63], v[30:31], v[90:93]
	v_mfma_f32_4x4x4_16b_f16 v[94:97], v[62:63], v[32:33], v[94:97]
	s_nop 1
	v_cvt_pkrtz_f16_f32 v68, v82, v83
	v_cvt_pkrtz_f16_f32 v69, v84, v85
	v_cvt_pkrtz_f16_f32 v70, v86, v87
	v_cvt_pkrtz_f16_f32 v71, v88, v89
	v_cvt_pkrtz_f16_f32 v72, v90, v91
	v_cvt_pkrtz_f16_f32 v73, v92, v93
	s_waitcnt lgkmcnt(8)
	v_mfma_f32_16x16x32_f16 v[64:67], v[2:5], v[68:71], 0
	v_cvt_pkrtz_f16_f32 v74, v94, v95
	v_cvt_pkrtz_f16_f32 v75, v96, v97
	s_nop 1
	v_mfma_f32_16x16x32_f16 v[64:67], v[6:9], v[72:75], v[64:67]
	v_add_u32_e32 v58, v156, v149
	ds_read_b128 v[98:101], v58
	ds_read_b128 v[102:105], v58 offset:64
	ds_read_b128 v[60:63], v59 offset:23808
	ds_read_b32 v29, v0 offset:32000
	s_waitcnt lgkmcnt(10)
	s_nop 1
	v_cvt_pkrtz_f16_f32 v30, v64, v26
	v_mov_b32_e32 v33, v30
	ds_write2st64_b32 v57, v65, v64 offset0:156 offset1:188
	v_mfma_f32_4x4x4_16b_f16 v[82:85], v[18:19], v[30:31], v[82:85]
	v_mfma_f32_4x4x4_16b_f16 v[86:89], v[18:19], v[32:33], v[86:89]
	v_mfma_f32_4x4x4_16b_f16 v[90:93], v[20:21], v[30:31], v[90:93]
	v_mfma_f32_4x4x4_16b_f16 v[94:97], v[20:21], v[32:33], v[94:97]
	s_nop 1
	v_cvt_pkrtz_f16_f32 v68, v82, v83
	v_cvt_pkrtz_f16_f32 v69, v84, v85
	v_cvt_pkrtz_f16_f32 v70, v86, v87
	v_cvt_pkrtz_f16_f32 v71, v88, v89
	v_cvt_pkrtz_f16_f32 v72, v90, v91
	v_cvt_pkrtz_f16_f32 v73, v92, v93
	s_waitcnt lgkmcnt(8)
	v_mfma_f32_16x16x32_f16 v[64:67], v[10:13], v[68:71], 0
	v_cvt_pkrtz_f16_f32 v74, v94, v95
	v_cvt_pkrtz_f16_f32 v75, v96, v97
	s_nop 1
	v_mfma_f32_16x16x32_f16 v[64:67], v[14:17], v[72:75], v[64:67]
	v_add_u32_e32 v58, v156, v150
	ds_read_b128 v[2:5], v58
	ds_read_b128 v[6:9], v58 offset:64
	ds_read_b128 v[18:21], v59 offset:24064
	ds_read_b32 v26, v0 offset:32256
	s_waitcnt lgkmcnt(10)
	s_nop 1
	v_cvt_pkrtz_f16_f32 v30, v64, v27
	v_mov_b32_e32 v33, v30
	ds_write2st64_b32 v57, v65, v64 offset0:157 offset1:189
	v_mfma_f32_4x4x4_16b_f16 v[82:85], v[22:23], v[30:31], v[82:85]
	v_mfma_f32_4x4x4_16b_f16 v[86:89], v[22:23], v[32:33], v[86:89]
	v_mfma_f32_4x4x4_16b_f16 v[90:93], v[24:25], v[30:31], v[90:93]
	v_mfma_f32_4x4x4_16b_f16 v[94:97], v[24:25], v[32:33], v[94:97]
	s_nop 1
	v_cvt_pkrtz_f16_f32 v68, v82, v83
	v_cvt_pkrtz_f16_f32 v69, v84, v85
	v_cvt_pkrtz_f16_f32 v70, v86, v87
	v_cvt_pkrtz_f16_f32 v71, v88, v89
	v_cvt_pkrtz_f16_f32 v72, v90, v91
	v_cvt_pkrtz_f16_f32 v73, v92, v93
	s_waitcnt lgkmcnt(8)
	v_mfma_f32_16x16x32_f16 v[64:67], v[98:101], v[68:71], 0
	v_cvt_pkrtz_f16_f32 v74, v94, v95
	v_cvt_pkrtz_f16_f32 v75, v96, v97
	s_nop 1
	v_mfma_f32_16x16x32_f16 v[64:67], v[102:105], v[72:75], v[64:67]
	v_add_u32_e32 v58, v156, v151
	ds_read_b128 v[10:13], v58
	ds_read_b128 v[14:17], v58 offset:64
	ds_read_b128 v[22:25], v59 offset:24320
	ds_read_b32 v27, v0 offset:32512
	s_waitcnt lgkmcnt(10)
	s_nop 1
	v_cvt_pkrtz_f16_f32 v30, v64, v29
	v_mov_b32_e32 v33, v30
	ds_write2st64_b32 v57, v65, v64 offset0:158 offset1:190
	v_mfma_f32_4x4x4_16b_f16 v[82:85], v[60:61], v[30:31], v[82:85]
	v_mfma_f32_4x4x4_16b_f16 v[86:89], v[60:61], v[32:33], v[86:89]
	v_mfma_f32_4x4x4_16b_f16 v[90:93], v[62:63], v[30:31], v[90:93]
	v_mfma_f32_4x4x4_16b_f16 v[94:97], v[62:63], v[32:33], v[94:97]
	s_nop 1
	v_cvt_pkrtz_f16_f32 v68, v82, v83
	v_cvt_pkrtz_f16_f32 v69, v84, v85
	v_cvt_pkrtz_f16_f32 v70, v86, v87
	v_cvt_pkrtz_f16_f32 v71, v88, v89
	v_cvt_pkrtz_f16_f32 v72, v90, v91
	v_cvt_pkrtz_f16_f32 v73, v92, v93
	s_waitcnt lgkmcnt(8)
	v_mfma_f32_16x16x32_f16 v[64:67], v[2:5], v[68:71], 0
	v_cvt_pkrtz_f16_f32 v74, v94, v95
	v_cvt_pkrtz_f16_f32 v75, v96, v97
	s_nop 1
	v_mfma_f32_16x16x32_f16 v[64:67], v[6:9], v[72:75], v[64:67]
	s_waitcnt lgkmcnt(6)
	s_nop 6
	v_cvt_pkrtz_f16_f32 v30, v64, v26
	v_mov_b32_e32 v33, v30
	ds_write2st64_b32 v57, v65, v64 offset0:159 offset1:191
	v_mfma_f32_4x4x4_16b_f16 v[82:85], v[18:19], v[30:31], v[82:85]
	v_mfma_f32_4x4x4_16b_f16 v[86:89], v[18:19], v[32:33], v[86:89]
	v_mfma_f32_4x4x4_16b_f16 v[90:93], v[20:21], v[30:31], v[90:93]
	v_mfma_f32_4x4x4_16b_f16 v[94:97], v[20:21], v[32:33], v[94:97]
	s_nop 1
	v_cvt_pkrtz_f16_f32 v68, v82, v83
	v_cvt_pkrtz_f16_f32 v69, v84, v85
	v_cvt_pkrtz_f16_f32 v70, v86, v87
	v_cvt_pkrtz_f16_f32 v71, v88, v89
	v_cvt_pkrtz_f16_f32 v72, v90, v91
	v_cvt_pkrtz_f16_f32 v73, v92, v93
	s_waitcnt lgkmcnt(4)
	v_mfma_f32_16x16x32_f16 v[64:67], v[10:13], v[68:71], 0
	v_cvt_pkrtz_f16_f32 v74, v94, v95
	v_cvt_pkrtz_f16_f32 v75, v96, v97
	s_nop 1
	v_mfma_f32_16x16x32_f16 v[64:67], v[14:17], v[72:75], v[64:67]
	s_waitcnt lgkmcnt(2)
	s_nop 6
	v_cvt_pkrtz_f16_f32 v30, v64, v27
	v_mov_b32_e32 v33, v30
	ds_write2st64_b32 v57, v65, v64 offset0:160 offset1:192
	v_mfma_f32_4x4x4_16b_f16 v[82:85], v[22:23], v[30:31], v[82:85]
	v_mfma_f32_4x4x4_16b_f16 v[86:89], v[22:23], v[32:33], v[86:89]
	v_mfma_f32_4x4x4_16b_f16 v[90:93], v[24:25], v[30:31], v[90:93]
	v_mfma_f32_4x4x4_16b_f16 v[94:97], v[24:25], v[32:33], v[94:97]
	s_nop 1
	v_mul_f32_e32 v82, v82, v40
	v_mul_f32_e32 v83, v83, v41
	v_mul_f32_e32 v84, v84, v42
	v_mul_f32_e32 v85, v85, v43
	v_mul_f32_e32 v86, v86, v44
	v_mul_f32_e32 v87, v87, v45
	v_mul_f32_e32 v88, v88, v46
	v_mul_f32_e32 v89, v89, v47
	v_mul_f32_e32 v90, v90, v48
	v_mul_f32_e32 v91, v91, v49
	v_mul_f32_e32 v92, v92, v50
	v_mul_f32_e32 v93, v93, v51
	v_mul_f32_e32 v94, v94, v52
	v_mul_f32_e32 v95, v95, v53
	v_mul_f32_e32 v96, v96, v54
	v_mul_f32_e32 v97, v97, v55
	s_add_i32 s8, s8, 1
	s_cmpk_lg_i32 s8, 0x80
	s_waitcnt lgkmcnt(0)
	s_barrier
	s_cbranch_scc1 .LBB0_120
	s_setprio 0
